# S5 pass C carry-in (Horner over previous chunk end states) by hand: wave-uniform count drives a scalar loop, running 64-bit address for the 16 loads per batch, three packed ops per step instead of mas
# speedup vs baseline: 1.0350x; 1.0006x over previous
.LBB0_1100:
	s_or_b64 exec, exec, s[8:9]
	v_and_b32_e32 v120, 31, v178
	v_lshlrev_b32_e32 v182, 10, v120
	v_lshlrev_b32_e32 v120, 10, v183
	v_lshl_add_u64 v[152:153], v[130:131], 0, v[120:121]
	v_cmp_ne_u32_e32 vcc, 0, v141
	s_and_saveexec_b64 s[66:67], vcc
	s_cbranch_execz .LBB0_1104
	v_ashrrev_i32_e32 v155, 31, v154
	v_lshlrev_b64 v[168:169], 15, v[154:155]
	v_or_b32_e32 v168, v168, v182
	s_waitcnt vmcnt(25)
	v_lshl_add_u64 v[168:169], v[130:131], 0, v[168:169]
	v_mov_b32_e32 v164, v86
	v_mov_b32_e32 v165, v86
	v_mov_b32_e32 v166, v87
	v_mov_b32_e32 v167, v87
	v_readfirstlane_b32 s70, v141
	s_mov_b32 s71, 0
	s_mov_b32 s74, 0x8000
	s_mov_b32 s75, 0
.Lhr0_b:
	s_cmp_ge_u32 s71, s70
	s_cbranch_scc1 .Lhr0_x
	global_load_dwordx2 v[184:185], v[168:169], off
	v_lshl_add_u64 v[168:169], v[168:169], 0, s[74:75]
	global_load_dwordx2 v[186:187], v[168:169], off
	v_lshl_add_u64 v[168:169], v[168:169], 0, s[74:75]
	global_load_dwordx2 v[188:189], v[168:169], off
	v_lshl_add_u64 v[168:169], v[168:169], 0, s[74:75]
	global_load_dwordx2 v[190:191], v[168:169], off
	v_lshl_add_u64 v[168:169], v[168:169], 0, s[74:75]
	global_load_dwordx2 v[192:193], v[168:169], off
	v_lshl_add_u64 v[168:169], v[168:169], 0, s[74:75]
	global_load_dwordx2 v[194:195], v[168:169], off
	v_lshl_add_u64 v[168:169], v[168:169], 0, s[74:75]
	global_load_dwordx2 v[196:197], v[168:169], off
	v_lshl_add_u64 v[168:169], v[168:169], 0, s[74:75]
	global_load_dwordx2 v[198:199], v[168:169], off
	v_lshl_add_u64 v[168:169], v[168:169], 0, s[74:75]
	global_load_dwordx2 v[200:201], v[168:169], off
	v_lshl_add_u64 v[168:169], v[168:169], 0, s[74:75]
	global_load_dwordx2 v[202:203], v[168:169], off
	v_lshl_add_u64 v[168:169], v[168:169], 0, s[74:75]
	global_load_dwordx2 v[204:205], v[168:169], off
	v_lshl_add_u64 v[168:169], v[168:169], 0, s[74:75]
	global_load_dwordx2 v[206:207], v[168:169], off
	v_lshl_add_u64 v[168:169], v[168:169], 0, s[74:75]
	global_load_dwordx2 v[208:209], v[168:169], off
	v_lshl_add_u64 v[168:169], v[168:169], 0, s[74:75]
	global_load_dwordx2 v[210:211], v[168:169], off
	v_lshl_add_u64 v[168:169], v[168:169], 0, s[74:75]
	global_load_dwordx2 v[212:213], v[168:169], off
	v_lshl_add_u64 v[168:169], v[168:169], 0, s[74:75]
	global_load_dwordx2 v[214:215], v[168:169], off
	v_lshl_add_u64 v[168:169], v[168:169], 0, s[74:75]
	s_waitcnt vmcnt(15)
	v_pk_mul_f32 v[216:217], v[166:167], v[160:161]
	v_pk_fma_f32 v[216:217], v[164:165], v[160:161], v[216:217] op_sel:[0,1,0] op_sel_hi:[1,0,1] neg_lo:[0,0,1]
	v_pk_add_f32 v[160:161], v[184:185], v[216:217] op_sel:[1,1] op_sel_hi:[0,0]
	s_add_i32 s71, s71, 1
	s_cmp_ge_u32 s71, s70
	s_cbranch_scc1 .Lhr0_d
	s_waitcnt vmcnt(14)
	v_pk_mul_f32 v[216:217], v[166:167], v[160:161]
	v_pk_fma_f32 v[216:217], v[164:165], v[160:161], v[216:217] op_sel:[0,1,0] op_sel_hi:[1,0,1] neg_lo:[0,0,1]
	v_pk_add_f32 v[160:161], v[186:187], v[216:217] op_sel:[1,1] op_sel_hi:[0,0]
	s_add_i32 s71, s71, 1
	s_cmp_ge_u32 s71, s70
	s_cbranch_scc1 .Lhr0_d
	s_waitcnt vmcnt(13)
	v_pk_mul_f32 v[216:217], v[166:167], v[160:161]
	v_pk_fma_f32 v[216:217], v[164:165], v[160:161], v[216:217] op_sel:[0,1,0] op_sel_hi:[1,0,1] neg_lo:[0,0,1]
	v_pk_add_f32 v[160:161], v[188:189], v[216:217] op_sel:[1,1] op_sel_hi:[0,0]
	s_add_i32 s71, s71, 1
	s_cmp_ge_u32 s71, s70
	s_cbranch_scc1 .Lhr0_d
	s_waitcnt vmcnt(12)
	v_pk_mul_f32 v[216:217], v[166:167], v[160:161]
	v_pk_fma_f32 v[216:217], v[164:165], v[160:161], v[216:217] op_sel:[0,1,0] op_sel_hi:[1,0,1] neg_lo:[0,0,1]
	v_pk_add_f32 v[160:161], v[190:191], v[216:217] op_sel:[1,1] op_sel_hi:[0,0]
	s_add_i32 s71, s71, 1
	s_cmp_ge_u32 s71, s70
	s_cbranch_scc1 .Lhr0_d
	s_waitcnt vmcnt(11)
	v_pk_mul_f32 v[216:217], v[166:167], v[160:161]
	v_pk_fma_f32 v[216:217], v[164:165], v[160:161], v[216:217] op_sel:[0,1,0] op_sel_hi:[1,0,1] neg_lo:[0,0,1]
	v_pk_add_f32 v[160:161], v[192:193], v[216:217] op_sel:[1,1] op_sel_hi:[0,0]
	s_add_i32 s71, s71, 1
	s_cmp_ge_u32 s71, s70
	s_cbranch_scc1 .Lhr0_d
	s_waitcnt vmcnt(10)
	v_pk_mul_f32 v[216:217], v[166:167], v[160:161]
	v_pk_fma_f32 v[216:217], v[164:165], v[160:161], v[216:217] op_sel:[0,1,0] op_sel_hi:[1,0,1] neg_lo:[0,0,1]
	v_pk_add_f32 v[160:161], v[194:195], v[216:217] op_sel:[1,1] op_sel_hi:[0,0]
	s_add_i32 s71, s71, 1
	s_cmp_ge_u32 s71, s70
	s_cbranch_scc1 .Lhr0_d
	s_waitcnt vmcnt(9)
	v_pk_mul_f32 v[216:217], v[166:167], v[160:161]
	v_pk_fma_f32 v[216:217], v[164:165], v[160:161], v[216:217] op_sel:[0,1,0] op_sel_hi:[1,0,1] neg_lo:[0,0,1]
	v_pk_add_f32 v[160:161], v[196:197], v[216:217] op_sel:[1,1] op_sel_hi:[0,0]
	s_add_i32 s71, s71, 1
	s_cmp_ge_u32 s71, s70
	s_cbranch_scc1 .Lhr0_d
	s_waitcnt vmcnt(8)
	v_pk_mul_f32 v[216:217], v[166:167], v[160:161]
	v_pk_fma_f32 v[216:217], v[164:165], v[160:161], v[216:217] op_sel:[0,1,0] op_sel_hi:[1,0,1] neg_lo:[0,0,1]
	v_pk_add_f32 v[160:161], v[198:199], v[216:217] op_sel:[1,1] op_sel_hi:[0,0]
	s_add_i32 s71, s71, 1
	s_cmp_ge_u32 s71, s70
	s_cbranch_scc1 .Lhr0_d
	s_waitcnt vmcnt(7)
	v_pk_mul_f32 v[216:217], v[166:167], v[160:161]
	v_pk_fma_f32 v[216:217], v[164:165], v[160:161], v[216:217] op_sel:[0,1,0] op_sel_hi:[1,0,1] neg_lo:[0,0,1]
	v_pk_add_f32 v[160:161], v[200:201], v[216:217] op_sel:[1,1] op_sel_hi:[0,0]
	s_add_i32 s71, s71, 1
	s_cmp_ge_u32 s71, s70
	s_cbranch_scc1 .Lhr0_d
	s_waitcnt vmcnt(6)
	v_pk_mul_f32 v[216:217], v[166:167], v[160:161]
	v_pk_fma_f32 v[216:217], v[164:165], v[160:161], v[216:217] op_sel:[0,1,0] op_sel_hi:[1,0,1] neg_lo:[0,0,1]
	v_pk_add_f32 v[160:161], v[202:203], v[216:217] op_sel:[1,1] op_sel_hi:[0,0]
	s_add_i32 s71, s71, 1
	s_cmp_ge_u32 s71, s70
	s_cbranch_scc1 .Lhr0_d
	s_waitcnt vmcnt(5)
	v_pk_mul_f32 v[216:217], v[166:167], v[160:161]
	v_pk_fma_f32 v[216:217], v[164:165], v[160:161], v[216:217] op_sel:[0,1,0] op_sel_hi:[1,0,1] neg_lo:[0,0,1]
	v_pk_add_f32 v[160:161], v[204:205], v[216:217] op_sel:[1,1] op_sel_hi:[0,0]
	s_add_i32 s71, s71, 1
	s_cmp_ge_u32 s71, s70
	s_cbranch_scc1 .Lhr0_d
	s_waitcnt vmcnt(4)
	v_pk_mul_f32 v[216:217], v[166:167], v[160:161]
	v_pk_fma_f32 v[216:217], v[164:165], v[160:161], v[216:217] op_sel:[0,1,0] op_sel_hi:[1,0,1] neg_lo:[0,0,1]
	v_pk_add_f32 v[160:161], v[206:207], v[216:217] op_sel:[1,1] op_sel_hi:[0,0]
	s_add_i32 s71, s71, 1
	s_cmp_ge_u32 s71, s70
	s_cbranch_scc1 .Lhr0_d
	s_waitcnt vmcnt(3)
	v_pk_mul_f32 v[216:217], v[166:167], v[160:161]
	v_pk_fma_f32 v[216:217], v[164:165], v[160:161], v[216:217] op_sel:[0,1,0] op_sel_hi:[1,0,1] neg_lo:[0,0,1]
	v_pk_add_f32 v[160:161], v[208:209], v[216:217] op_sel:[1,1] op_sel_hi:[0,0]
	s_add_i32 s71, s71, 1
	s_cmp_ge_u32 s71, s70
	s_cbranch_scc1 .Lhr0_d
	s_waitcnt vmcnt(2)
	v_pk_mul_f32 v[216:217], v[166:167], v[160:161]
	v_pk_fma_f32 v[216:217], v[164:165], v[160:161], v[216:217] op_sel:[0,1,0] op_sel_hi:[1,0,1] neg_lo:[0,0,1]
	v_pk_add_f32 v[160:161], v[210:211], v[216:217] op_sel:[1,1] op_sel_hi:[0,0]
	s_add_i32 s71, s71, 1
	s_cmp_ge_u32 s71, s70
	s_cbranch_scc1 .Lhr0_d
	s_waitcnt vmcnt(1)
	v_pk_mul_f32 v[216:217], v[166:167], v[160:161]
	v_pk_fma_f32 v[216:217], v[164:165], v[160:161], v[216:217] op_sel:[0,1,0] op_sel_hi:[1,0,1] neg_lo:[0,0,1]
	v_pk_add_f32 v[160:161], v[212:213], v[216:217] op_sel:[1,1] op_sel_hi:[0,0]
	s_add_i32 s71, s71, 1
	s_cmp_ge_u32 s71, s70
	s_cbranch_scc1 .Lhr0_d
	s_waitcnt vmcnt(0)
	v_pk_mul_f32 v[216:217], v[166:167], v[160:161]
	v_pk_fma_f32 v[216:217], v[164:165], v[160:161], v[216:217] op_sel:[0,1,0] op_sel_hi:[1,0,1] neg_lo:[0,0,1]
	v_pk_add_f32 v[160:161], v[214:215], v[216:217] op_sel:[1,1] op_sel_hi:[0,0]
	s_add_i32 s71, s71, 1
	s_branch .Lhr0_b

.Lhr0_x:
.LBB0_1104:
	s_or_b64 exec, exec, s[66:67]
	s_waitcnt vmcnt(24)
	v_mfma_f32_16x16x32_bf16 v[162:165], v[116:119], v[48:51], 0
	s_waitcnt lgkmcnt(0)
	v_lshlrev_b32_e32 v155, 4, v183
	s_mov_b32 s8, 0
	s_waitcnt vmcnt(23)
	v_mfma_f32_16x16x32_bf16 v[166:169], v[112:115], v[48:51], 0
	s_waitcnt vmcnt(22)
	v_mfma_f32_16x16x32_bf16 v[184:187], v[108:111], v[48:51], 0
	s_nop 1
	v_cvt_pk_bf16_f32 v86, v162, v163
	v_cvt_pk_bf16_f32 v87, v164, v165
	s_nop 1
	v_cvt_pk_bf16_f32 v166, v166, v167
	s_waitcnt vmcnt(21)
	v_mfma_f32_16x16x32_bf16 v[188:191], v[104:107], v[48:51], 0
	v_cvt_pk_bf16_f32 v167, v168, v169
	ds_write2_b64 v179, v[86:87], v[166:167] offset1:4
	v_cvt_pk_bf16_f32 v86, v184, v185
	s_waitcnt vmcnt(20)
	v_mfma_f32_16x16x32_bf16 v[192:195], v[100:103], v[48:51], 0
	v_cvt_pk_bf16_f32 v87, v186, v187
	s_nop 1
	v_cvt_pk_bf16_f32 v188, v188, v189
	v_cvt_pk_bf16_f32 v189, v190, v191
	s_waitcnt vmcnt(19)
	v_mfma_f32_16x16x32_bf16 v[162:165], v[96:99], v[48:51], 0
	ds_write2_b64 v179, v[86:87], v[188:189] offset0:8 offset1:12
	v_cvt_pk_bf16_f32 v86, v192, v193
	v_cvt_pk_bf16_f32 v87, v194, v195
	s_waitcnt vmcnt(18)
	v_mfma_f32_16x16x32_bf16 v[166:169], v[88:91], v[48:51], 0
	s_waitcnt vmcnt(17)
	v_mfma_f32_16x16x32_bf16 v[184:187], v[92:95], v[48:51], 0
	s_nop 0
	v_cvt_pk_bf16_f32 v192, v162, v163
	v_cvt_pk_bf16_f32 v193, v164, v165
	ds_write2_b64 v179, v[86:87], v[192:193] offset0:16 offset1:20
	v_mfma_f32_16x16x32_bf16 v[188:191], v[116:119], v[24:27], 0
	s_nop 0
	v_cvt_pk_bf16_f32 v86, v166, v167
	v_cvt_pk_bf16_f32 v87, v168, v169
	v_cvt_pk_bf16_f32 v184, v184, v185
	v_mfma_f32_16x16x32_bf16 v[162:165], v[112:115], v[24:27], 0
	v_cvt_pk_bf16_f32 v185, v186, v187
	ds_write2_b64 v179, v[86:87], v[184:185] offset0:24 offset1:28
	s_nop 0
	v_cvt_pk_bf16_f32 v86, v188, v189
	v_mfma_f32_16x16x32_bf16 v[166:169], v[108:111], v[24:27], 0
	v_cvt_pk_bf16_f32 v87, v190, v191
	s_nop 1
	v_cvt_pk_bf16_f32 v192, v162, v163
	v_cvt_pk_bf16_f32 v193, v164, v165
	v_mfma_f32_16x16x32_bf16 v[184:187], v[104:107], v[24:27], 0
	v_add_u32_e32 v162, 0x1000, v179
	ds_write2_b64 v162, v[86:87], v[192:193] offset0:32 offset1:36
	v_cvt_pk_bf16_f32 v86, v166, v167
	v_mfma_f32_16x16x32_bf16 v[188:191], v[100:103], v[24:27], 0
	v_cvt_pk_bf16_f32 v87, v168, v169
	s_nop 2
	v_cvt_pk_bf16_f32 v168, v184, v185
	v_cvt_pk_bf16_f32 v169, v186, v187
	v_mfma_f32_16x16x32_bf16 v[192:195], v[96:99], v[24:27], 0
	ds_write2_b64 v162, v[86:87], v[168:169] offset0:40 offset1:44
	v_cvt_pk_bf16_f32 v86, v188, v189
	v_cvt_pk_bf16_f32 v87, v190, v191
	v_mfma_f32_16x16x32_bf16 v[164:167], v[88:91], v[24:27], 0
	v_add_u32_e32 v163, 0x2000, v179
	s_nop 2
	v_cvt_pk_bf16_f32 v168, v192, v193
	v_cvt_pk_bf16_f32 v169, v194, v195
	v_mfma_f32_16x16x32_bf16 v[184:187], v[92:95], v[24:27], 0
	ds_write2_b64 v162, v[86:87], v[168:169] offset0:48 offset1:52
	v_cvt_pk_bf16_f32 v86, v164, v165
	v_cvt_pk_bf16_f32 v87, v166, v167
	v_mfma_f32_16x16x32_bf16 v[188:191], v[116:119], v[28:31], 0
	v_mfma_f32_16x16x32_bf16 v[164:167], v[112:115], v[28:31], 0
	s_nop 2
	v_cvt_pk_bf16_f32 v168, v184, v185
	v_cvt_pk_bf16_f32 v169, v186, v187
	ds_write2_b64 v162, v[86:87], v[168:169] offset0:56 offset1:60
	v_mfma_f32_16x16x32_bf16 v[184:187], v[108:111], v[28:31], 0
	v_cvt_pk_bf16_f32 v86, v188, v189
	v_cvt_pk_bf16_f32 v87, v190, v191
	v_cvt_pk_bf16_f32 v164, v164, v165
	v_mfma_f32_16x16x32_bf16 v[188:191], v[104:107], v[28:31], 0
	v_cvt_pk_bf16_f32 v165, v166, v167
	ds_write2_b64 v163, v[86:87], v[164:165] offset0:64 offset1:68
	s_nop 1
	v_cvt_pk_bf16_f32 v86, v184, v185
	v_mfma_f32_16x16x32_bf16 v[164:167], v[100:103], v[28:31], 0
	v_cvt_pk_bf16_f32 v87, v186, v187
	s_nop 0
	v_cvt_pk_bf16_f32 v168, v188, v189
	v_cvt_pk_bf16_f32 v169, v190, v191
	v_mfma_f32_16x16x32_bf16 v[184:187], v[96:99], v[28:31], 0
	ds_write2_b64 v163, v[86:87], v[168:169] offset0:72 offset1:76
	s_nop 1
	v_cvt_pk_bf16_f32 v86, v164, v165
	v_cvt_pk_bf16_f32 v87, v166, v167
	v_mfma_f32_16x16x32_bf16 v[188:191], v[88:91], v[28:31], 0
	v_mfma_f32_16x16x32_bf16 v[164:167], v[92:95], v[28:31], 0
	s_nop 0
	v_cvt_pk_bf16_f32 v168, v184, v185
	v_cvt_pk_bf16_f32 v169, v186, v187
	ds_write2_b64 v163, v[86:87], v[168:169] offset0:80 offset1:84
	v_mfma_f32_16x16x32_bf16 v[116:119], v[116:119], v[20:23], 0
	s_nop 1
	v_cvt_pk_bf16_f32 v86, v188, v189
	v_cvt_pk_bf16_f32 v87, v190, v191
	v_cvt_pk_bf16_f32 v164, v164, v165
	v_mfma_f32_16x16x32_bf16 v[112:115], v[112:115], v[20:23], 0
	v_cvt_pk_bf16_f32 v165, v166, v167
	ds_write2_b64 v163, v[86:87], v[164:165] offset0:88 offset1:92
	v_cvt_pk_bf16_f32 v86, v116, v117
	v_mfma_f32_16x16x32_bf16 v[104:107], v[104:107], v[20:23], 0
	v_cvt_pk_bf16_f32 v87, v118, v119
	s_nop 2
	v_cvt_pk_bf16_f32 v116, v112, v113
	v_cvt_pk_bf16_f32 v117, v114, v115
	v_mfma_f32_16x16x32_bf16 v[110:113], v[108:111], v[20:23], 0
	v_add_u32_e32 v108, 0x3000, v179
	ds_write2_b64 v108, v[86:87], v[116:117] offset0:96 offset1:100
	v_cvt_pk_bf16_f32 v104, v104, v105
	v_cvt_pk_bf16_f32 v105, v106, v107
	v_mfma_f32_16x16x32_bf16 v[100:103], v[100:103], v[20:23], 0
	s_nop 2
	v_cvt_pk_bf16_f32 v86, v110, v111
	v_cvt_pk_bf16_f32 v87, v112, v113
	ds_write2_b64 v108, v[86:87], v[104:105] offset0:104 offset1:108
	v_mfma_f32_16x16x32_bf16 v[86:89], v[88:91], v[20:23], 0
	v_mfma_f32_16x16x32_bf16 v[96:99], v[96:99], v[20:23], 0
	v_cvt_pk_bf16_f32 v100, v100, v101
	s_nop 5
	v_cvt_pk_bf16_f32 v90, v86, v87
	v_cvt_pk_bf16_f32 v91, v88, v89
	v_mfma_f32_16x16x32_bf16 v[86:89], v[92:95], v[20:23], 0
	v_cvt_pk_bf16_f32 v101, v102, v103
	v_cvt_pk_bf16_f32 v96, v96, v97
	v_cvt_pk_bf16_f32 v97, v98, v99
	ds_write2_b64 v108, v[100:101], v[96:97] offset0:112 offset1:116
	s_nop 3
	v_cvt_pk_bf16_f32 v86, v86, v87
	v_cvt_pk_bf16_f32 v87, v88, v89
	ds_write2_b64 v108, v[90:91], v[86:87] offset0:120 offset1:124
	s_waitcnt lgkmcnt(0)
	v_xor_b32_e32 v87, 0x80000000, v85
	v_mov_b32_e32 v86, v85
	v_mov_b32_e32 v88, v84
	v_mov_b32_e32 v89, v84
	v_mov_b32_e32 v84, v87
	v_pk_mov_b32 v[90:91], v[86:87], v[86:87] op_sel:[1,0]
	v_pk_mov_b32 v[92:93], v[84:85], v[84:85] op_sel:[1,0]

.LBB0_1110:
	s_or_b64 exec, exec, s[8:9]
	v_xad_u32 v99, v141, -1, v181
	v_cmp_lt_i32_e32 vcc, 0, v99
	s_and_saveexec_b64 s[66:67], vcc
	s_cbranch_execz .LBB0_1114
	v_add_u32_e32 v76, v76, v154
	v_ashrrev_i32_e32 v77, 31, v76
	v_lshlrev_b64 v[96:97], 15, v[76:77]
	v_or_b32_e32 v96, v96, v182
	s_waitcnt vmcnt(12)
	v_lshl_add_u64 v[96:97], v[136:137], 0, v[96:97]
	v_mov_b32_e32 v80, v18
	v_mov_b32_e32 v81, v18
	v_mov_b32_e32 v82, v19
	v_mov_b32_e32 v83, v19
	v_readfirstlane_b32 s70, v99
	s_mov_b32 s71, 0
	s_mov_b32 s74, 0xffff8000
	s_mov_b32 s75, -1
.Lhr1_b:
	s_cmp_ge_u32 s71, s70
	s_cbranch_scc1 .Lhr1_x
	global_load_dwordx2 v[100:101], v[96:97], off
	v_lshl_add_u64 v[96:97], v[96:97], 0, s[74:75]
	global_load_dwordx2 v[102:103], v[96:97], off
	v_lshl_add_u64 v[96:97], v[96:97], 0, s[74:75]
	global_load_dwordx2 v[104:105], v[96:97], off
	v_lshl_add_u64 v[96:97], v[96:97], 0, s[74:75]
	global_load_dwordx2 v[106:107], v[96:97], off
	v_lshl_add_u64 v[96:97], v[96:97], 0, s[74:75]
	global_load_dwordx2 v[110:111], v[96:97], off
	v_lshl_add_u64 v[96:97], v[96:97], 0, s[74:75]
	global_load_dwordx2 v[112:113], v[96:97], off
	v_lshl_add_u64 v[96:97], v[96:97], 0, s[74:75]
	global_load_dwordx2 v[114:115], v[96:97], off
	v_lshl_add_u64 v[96:97], v[96:97], 0, s[74:75]
	global_load_dwordx2 v[116:117], v[96:97], off
	v_lshl_add_u64 v[96:97], v[96:97], 0, s[74:75]
	global_load_dwordx2 v[118:119], v[96:97], off
	v_lshl_add_u64 v[96:97], v[96:97], 0, s[74:75]
	global_load_dwordx2 v[156:157], v[96:97], off
	v_lshl_add_u64 v[96:97], v[96:97], 0, s[74:75]
	global_load_dwordx2 v[158:159], v[96:97], off
	v_lshl_add_u64 v[96:97], v[96:97], 0, s[74:75]
	global_load_dwordx2 v[160:161], v[96:97], off
	v_lshl_add_u64 v[96:97], v[96:97], 0, s[74:75]
	global_load_dwordx2 v[164:165], v[96:97], off
	v_lshl_add_u64 v[96:97], v[96:97], 0, s[74:75]
	global_load_dwordx2 v[166:167], v[96:97], off
	v_lshl_add_u64 v[96:97], v[96:97], 0, s[74:75]
	global_load_dwordx2 v[168:169], v[96:97], off
	v_lshl_add_u64 v[96:97], v[96:97], 0, s[74:75]
	global_load_dwordx2 v[184:185], v[96:97], off
	v_lshl_add_u64 v[96:97], v[96:97], 0, s[74:75]
	s_waitcnt vmcnt(15)
	v_pk_mul_f32 v[182:183], v[82:83], v[74:75]
	v_pk_fma_f32 v[182:183], v[80:81], v[74:75], v[182:183] op_sel:[0,1,0] op_sel_hi:[1,0,1] neg_lo:[0,0,1]
	v_pk_add_f32 v[74:75], v[100:101], v[182:183] op_sel:[1,1] op_sel_hi:[0,0]
	s_add_i32 s71, s71, 1
	s_cmp_ge_u32 s71, s70
	s_cbranch_scc1 .Lhr1_d
	s_waitcnt vmcnt(14)
	v_pk_mul_f32 v[182:183], v[82:83], v[74:75]
	v_pk_fma_f32 v[182:183], v[80:81], v[74:75], v[182:183] op_sel:[0,1,0] op_sel_hi:[1,0,1] neg_lo:[0,0,1]
	v_pk_add_f32 v[74:75], v[102:103], v[182:183] op_sel:[1,1] op_sel_hi:[0,0]
	s_add_i32 s71, s71, 1
	s_cmp_ge_u32 s71, s70
	s_cbranch_scc1 .Lhr1_d
	s_waitcnt vmcnt(13)
	v_pk_mul_f32 v[182:183], v[82:83], v[74:75]
	v_pk_fma_f32 v[182:183], v[80:81], v[74:75], v[182:183] op_sel:[0,1,0] op_sel_hi:[1,0,1] neg_lo:[0,0,1]
	v_pk_add_f32 v[74:75], v[104:105], v[182:183] op_sel:[1,1] op_sel_hi:[0,0]
	s_add_i32 s71, s71, 1
	s_cmp_ge_u32 s71, s70
	s_cbranch_scc1 .Lhr1_d
	s_waitcnt vmcnt(12)
	v_pk_mul_f32 v[182:183], v[82:83], v[74:75]
	v_pk_fma_f32 v[182:183], v[80:81], v[74:75], v[182:183] op_sel:[0,1,0] op_sel_hi:[1,0,1] neg_lo:[0,0,1]
	v_pk_add_f32 v[74:75], v[106:107], v[182:183] op_sel:[1,1] op_sel_hi:[0,0]
	s_add_i32 s71, s71, 1
	s_cmp_ge_u32 s71, s70
	s_cbranch_scc1 .Lhr1_d
	s_waitcnt vmcnt(11)
	v_pk_mul_f32 v[182:183], v[82:83], v[74:75]
	v_pk_fma_f32 v[182:183], v[80:81], v[74:75], v[182:183] op_sel:[0,1,0] op_sel_hi:[1,0,1] neg_lo:[0,0,1]
	v_pk_add_f32 v[74:75], v[110:111], v[182:183] op_sel:[1,1] op_sel_hi:[0,0]
	s_add_i32 s71, s71, 1
	s_cmp_ge_u32 s71, s70
	s_cbranch_scc1 .Lhr1_d
	s_waitcnt vmcnt(10)
	v_pk_mul_f32 v[182:183], v[82:83], v[74:75]
	v_pk_fma_f32 v[182:183], v[80:81], v[74:75], v[182:183] op_sel:[0,1,0] op_sel_hi:[1,0,1] neg_lo:[0,0,1]
	v_pk_add_f32 v[74:75], v[112:113], v[182:183] op_sel:[1,1] op_sel_hi:[0,0]
	s_add_i32 s71, s71, 1
	s_cmp_ge_u32 s71, s70
	s_cbranch_scc1 .Lhr1_d
	s_waitcnt vmcnt(9)
	v_pk_mul_f32 v[182:183], v[82:83], v[74:75]
	v_pk_fma_f32 v[182:183], v[80:81], v[74:75], v[182:183] op_sel:[0,1,0] op_sel_hi:[1,0,1] neg_lo:[0,0,1]
	v_pk_add_f32 v[74:75], v[114:115], v[182:183] op_sel:[1,1] op_sel_hi:[0,0]
	s_add_i32 s71, s71, 1
	s_cmp_ge_u32 s71, s70
	s_cbranch_scc1 .Lhr1_d
	s_waitcnt vmcnt(8)
	v_pk_mul_f32 v[182:183], v[82:83], v[74:75]
	v_pk_fma_f32 v[182:183], v[80:81], v[74:75], v[182:183] op_sel:[0,1,0] op_sel_hi:[1,0,1] neg_lo:[0,0,1]
	v_pk_add_f32 v[74:75], v[116:117], v[182:183] op_sel:[1,1] op_sel_hi:[0,0]
	s_add_i32 s71, s71, 1
	s_cmp_ge_u32 s71, s70
	s_cbranch_scc1 .Lhr1_d
	s_waitcnt vmcnt(7)
	v_pk_mul_f32 v[182:183], v[82:83], v[74:75]
	v_pk_fma_f32 v[182:183], v[80:81], v[74:75], v[182:183] op_sel:[0,1,0] op_sel_hi:[1,0,1] neg_lo:[0,0,1]
	v_pk_add_f32 v[74:75], v[118:119], v[182:183] op_sel:[1,1] op_sel_hi:[0,0]
	s_add_i32 s71, s71, 1
	s_cmp_ge_u32 s71, s70
	s_cbranch_scc1 .Lhr1_d
	s_waitcnt vmcnt(6)
	v_pk_mul_f32 v[182:183], v[82:83], v[74:75]
	v_pk_fma_f32 v[182:183], v[80:81], v[74:75], v[182:183] op_sel:[0,1,0] op_sel_hi:[1,0,1] neg_lo:[0,0,1]
	v_pk_add_f32 v[74:75], v[156:157], v[182:183] op_sel:[1,1] op_sel_hi:[0,0]
	s_add_i32 s71, s71, 1
	s_cmp_ge_u32 s71, s70
	s_cbranch_scc1 .Lhr1_d
	s_waitcnt vmcnt(5)
	v_pk_mul_f32 v[182:183], v[82:83], v[74:75]
	v_pk_fma_f32 v[182:183], v[80:81], v[74:75], v[182:183] op_sel:[0,1,0] op_sel_hi:[1,0,1] neg_lo:[0,0,1]
	v_pk_add_f32 v[74:75], v[158:159], v[182:183] op_sel:[1,1] op_sel_hi:[0,0]
	s_add_i32 s71, s71, 1
	s_cmp_ge_u32 s71, s70
	s_cbranch_scc1 .Lhr1_d
	s_waitcnt vmcnt(4)
	v_pk_mul_f32 v[182:183], v[82:83], v[74:75]
	v_pk_fma_f32 v[182:183], v[80:81], v[74:75], v[182:183] op_sel:[0,1,0] op_sel_hi:[1,0,1] neg_lo:[0,0,1]
	v_pk_add_f32 v[74:75], v[160:161], v[182:183] op_sel:[1,1] op_sel_hi:[0,0]
	s_add_i32 s71, s71, 1
	s_cmp_ge_u32 s71, s70
	s_cbranch_scc1 .Lhr1_d
	s_waitcnt vmcnt(3)
	v_pk_mul_f32 v[182:183], v[82:83], v[74:75]
	v_pk_fma_f32 v[182:183], v[80:81], v[74:75], v[182:183] op_sel:[0,1,0] op_sel_hi:[1,0,1] neg_lo:[0,0,1]
	v_pk_add_f32 v[74:75], v[164:165], v[182:183] op_sel:[1,1] op_sel_hi:[0,0]
	s_add_i32 s71, s71, 1
	s_cmp_ge_u32 s71, s70
	s_cbranch_scc1 .Lhr1_d
	s_waitcnt vmcnt(2)
	v_pk_mul_f32 v[182:183], v[82:83], v[74:75]
	v_pk_fma_f32 v[182:183], v[80:81], v[74:75], v[182:183] op_sel:[0,1,0] op_sel_hi:[1,0,1] neg_lo:[0,0,1]
	v_pk_add_f32 v[74:75], v[166:167], v[182:183] op_sel:[1,1] op_sel_hi:[0,0]
	s_add_i32 s71, s71, 1
	s_cmp_ge_u32 s71, s70
	s_cbranch_scc1 .Lhr1_d
	s_waitcnt vmcnt(1)
	v_pk_mul_f32 v[182:183], v[82:83], v[74:75]
	v_pk_fma_f32 v[182:183], v[80:81], v[74:75], v[182:183] op_sel:[0,1,0] op_sel_hi:[1,0,1] neg_lo:[0,0,1]
	v_pk_add_f32 v[74:75], v[168:169], v[182:183] op_sel:[1,1] op_sel_hi:[0,0]
	s_add_i32 s71, s71, 1
	s_cmp_ge_u32 s71, s70
	s_cbranch_scc1 .Lhr1_d
	s_waitcnt vmcnt(0)
	v_pk_mul_f32 v[182:183], v[82:83], v[74:75]
	v_pk_fma_f32 v[182:183], v[80:81], v[74:75], v[182:183] op_sel:[0,1,0] op_sel_hi:[1,0,1] neg_lo:[0,0,1]
	v_pk_add_f32 v[74:75], v[184:185], v[182:183] op_sel:[1,1] op_sel_hi:[0,0]
	s_add_i32 s71, s71, 1
	s_branch .Lhr1_b

.Lhr1_x:
.LBB0_1114:
	s_or_b64 exec, exec, s[66:67]
	s_waitcnt vmcnt(11)
	v_mfma_f32_16x16x32_bf16 v[76:79], v[64:67], v[48:51], 0
	s_waitcnt lgkmcnt(0)
	s_movk_i32 s6, 0x3300
	s_waitcnt vmcnt(10)
	v_mfma_f32_16x16x32_bf16 v[80:83], v[60:63], v[48:51], 0
	s_waitcnt vmcnt(9)
	v_mfma_f32_16x16x32_bf16 v[96:99], v[56:59], v[48:51], 0
	s_nop 2
	v_cvt_pk_bf16_f32 v18, v76, v77
	v_cvt_pk_bf16_f32 v19, v78, v79
	s_nop 0
	v_cvt_pk_bf16_f32 v80, v80, v81
	s_waitcnt vmcnt(8)
	v_mfma_f32_16x16x32_bf16 v[100:103], v[52:55], v[48:51], 0
	v_cvt_pk_bf16_f32 v81, v82, v83
	ds_write2_b64 v179, v[18:19], v[80:81] offset1:4
	v_cvt_pk_bf16_f32 v18, v96, v97
	s_waitcnt vmcnt(7)
	v_mfma_f32_16x16x32_bf16 v[104:107], v[44:47], v[48:51], 0
	v_cvt_pk_bf16_f32 v19, v98, v99
	s_nop 1
	v_cvt_pk_bf16_f32 v96, v100, v101
	v_cvt_pk_bf16_f32 v97, v102, v103
	s_waitcnt vmcnt(6)
	v_mfma_f32_16x16x32_bf16 v[110:113], v[40:43], v[48:51], 0
	ds_write2_b64 v179, v[18:19], v[96:97] offset0:8 offset1:12
	v_cvt_pk_bf16_f32 v18, v104, v105
	v_cvt_pk_bf16_f32 v19, v106, v107
	s_waitcnt vmcnt(5)
	v_mfma_f32_16x16x32_bf16 v[76:79], v[36:39], v[48:51], 0
	s_waitcnt vmcnt(4)
	v_mfma_f32_16x16x32_bf16 v[48:51], v[32:35], v[48:51], 0
	s_nop 0
	v_cvt_pk_bf16_f32 v104, v110, v111
	v_cvt_pk_bf16_f32 v105, v112, v113
	ds_write2_b64 v179, v[18:19], v[104:105] offset0:16 offset1:20
	v_mfma_f32_16x16x32_bf16 v[80:83], v[64:67], v[24:27], 0
	s_nop 0
	v_cvt_pk_bf16_f32 v18, v76, v77
	v_cvt_pk_bf16_f32 v19, v78, v79
	v_cvt_pk_bf16_f32 v48, v48, v49
	v_mfma_f32_16x16x32_bf16 v[96:99], v[60:63], v[24:27], 0
	v_cvt_pk_bf16_f32 v49, v50, v51
	ds_write2_b64 v179, v[18:19], v[48:49] offset0:24 offset1:28
	s_nop 0
	v_cvt_pk_bf16_f32 v18, v80, v81
	v_mfma_f32_16x16x32_bf16 v[100:103], v[56:59], v[24:27], 0
	v_cvt_pk_bf16_f32 v19, v82, v83
	s_nop 1
	v_cvt_pk_bf16_f32 v96, v96, v97
	v_cvt_pk_bf16_f32 v97, v98, v99
	v_mfma_f32_16x16x32_bf16 v[76:79], v[52:55], v[24:27], 0
	ds_write2_b64 v162, v[18:19], v[96:97] offset0:32 offset1:36
	s_nop 0
	v_cvt_pk_bf16_f32 v18, v100, v101
	v_cvt_pk_bf16_f32 v19, v102, v103
	v_mfma_f32_16x16x32_bf16 v[48:51], v[44:47], v[24:27], 0
	v_mfma_f32_16x16x32_bf16 v[80:83], v[40:43], v[24:27], 0
	s_nop 1
	v_cvt_pk_bf16_f32 v76, v76, v77
	v_cvt_pk_bf16_f32 v77, v78, v79
	ds_write2_b64 v162, v[18:19], v[76:77] offset0:40 offset1:44
	v_mfma_f32_16x16x32_bf16 v[96:99], v[36:39], v[24:27], 0
	s_nop 0
	v_cvt_pk_bf16_f32 v18, v48, v49
	v_cvt_pk_bf16_f32 v19, v50, v51
	v_cvt_pk_bf16_f32 v76, v80, v81
	v_mfma_f32_16x16x32_bf16 v[24:27], v[32:35], v[24:27], 0
	v_cvt_pk_bf16_f32 v77, v82, v83
	ds_write2_b64 v162, v[18:19], v[76:77] offset0:48 offset1:52
	s_nop 0
	v_cvt_pk_bf16_f32 v18, v96, v97
	v_mfma_f32_16x16x32_bf16 v[48:51], v[64:67], v[28:31], 0
	v_cvt_pk_bf16_f32 v19, v98, v99
	s_nop 1
	v_cvt_pk_bf16_f32 v24, v24, v25
	v_cvt_pk_bf16_f32 v25, v26, v27
	v_mfma_f32_16x16x32_bf16 v[76:79], v[60:63], v[28:31], 0
	ds_write2_b64 v162, v[18:19], v[24:25] offset0:56 offset1:60
	s_nop 0
	v_cvt_pk_bf16_f32 v18, v48, v49
	v_cvt_pk_bf16_f32 v19, v50, v51
	v_mfma_f32_16x16x32_bf16 v[80:83], v[56:59], v[28:31], 0
	v_mfma_f32_16x16x32_bf16 v[24:27], v[52:55], v[28:31], 0
	s_nop 1
	v_cvt_pk_bf16_f32 v76, v76, v77
	v_cvt_pk_bf16_f32 v77, v78, v79
	ds_write2_b64 v163, v[18:19], v[76:77] offset0:64 offset1:68
	v_mfma_f32_16x16x32_bf16 v[48:51], v[44:47], v[28:31], 0
	s_nop 0
	v_cvt_pk_bf16_f32 v18, v80, v81
	v_cvt_pk_bf16_f32 v19, v82, v83
	v_cvt_pk_bf16_f32 v24, v24, v25
	v_mfma_f32_16x16x32_bf16 v[76:79], v[40:43], v[28:31], 0
	v_cvt_pk_bf16_f32 v25, v26, v27
	ds_write2_b64 v163, v[18:19], v[24:25] offset0:72 offset1:76
	s_nop 0
	v_cvt_pk_bf16_f32 v18, v48, v49
	v_mfma_f32_16x16x32_bf16 v[24:27], v[36:39], v[28:31], 0
	v_cvt_pk_bf16_f32 v19, v50, v51
	s_nop 1
	v_cvt_pk_bf16_f32 v48, v76, v77
	v_cvt_pk_bf16_f32 v49, v78, v79
	v_mfma_f32_16x16x32_bf16 v[28:31], v[32:35], v[28:31], 0
	ds_write2_b64 v163, v[18:19], v[48:49] offset0:80 offset1:84
	s_nop 0
	v_cvt_pk_bf16_f32 v18, v24, v25
	v_cvt_pk_bf16_f32 v19, v26, v27
	v_mfma_f32_16x16x32_bf16 v[48:51], v[64:67], v[20:23], 0
	v_mfma_f32_16x16x32_bf16 v[24:27], v[60:63], v[20:23], 0
	s_nop 1
	v_cvt_pk_bf16_f32 v28, v28, v29
	v_cvt_pk_bf16_f32 v29, v30, v31
	ds_write2_b64 v163, v[18:19], v[28:29] offset0:88 offset1:92
	s_nop 1
	v_cvt_pk_bf16_f32 v18, v48, v49
	v_cvt_pk_bf16_f32 v19, v50, v51
	v_cvt_pk_bf16_f32 v24, v24, v25
	v_cvt_pk_bf16_f32 v25, v26, v27
	v_mfma_f32_16x16x32_bf16 v[28:31], v[56:59], v[20:23], 0
	ds_write2_b64 v108, v[18:19], v[24:25] offset0:96 offset1:100
	v_mfma_f32_16x16x32_bf16 v[24:27], v[52:55], v[20:23], 0
	s_nop 5
	v_cvt_pk_bf16_f32 v18, v28, v29
	v_cvt_pk_bf16_f32 v19, v30, v31
	v_cvt_pk_bf16_f32 v24, v24, v25
	v_cvt_pk_bf16_f32 v25, v26, v27
	v_mfma_f32_16x16x32_bf16 v[28:31], v[44:47], v[20:23], 0
	ds_write2_b64 v108, v[18:19], v[24:25] offset0:104 offset1:108
	v_mfma_f32_16x16x32_bf16 v[24:27], v[40:43], v[20:23], 0
	s_nop 5
	v_cvt_pk_bf16_f32 v18, v28, v29
	v_cvt_pk_bf16_f32 v19, v30, v31
	v_cvt_pk_bf16_f32 v28, v24, v25
	v_cvt_pk_bf16_f32 v29, v26, v27
	v_mfma_f32_16x16x32_bf16 v[24:27], v[36:39], v[20:23], 0
	ds_write2_b64 v108, v[18:19], v[28:29] offset0:112 offset1:116
	v_mfma_f32_16x16x32_bf16 v[18:21], v[32:35], v[20:23], 0
	s_nop 5
	v_cvt_pk_bf16_f32 v24, v24, v25
	v_cvt_pk_bf16_f32 v25, v26, v27
	v_cvt_pk_bf16_f32 v18, v18, v19
	v_cvt_pk_bf16_f32 v19, v20, v21
	ds_write2_b64 v108, v[24:25], v[18:19] offset0:120 offset1:124
	s_waitcnt lgkmcnt(0)
	v_xor_b32_e32 v19, 0x80000000, v17
	v_mov_b32_e32 v18, v17
	v_mov_b32_e32 v20, v16
	v_mov_b32_e32 v21, v16
	v_mov_b32_e32 v16, v19
	v_pk_mov_b32 v[22:23], v[18:19], v[18:19] op_sel:[1,0]
	v_pk_mov_b32 v[24:25], v[16:17], v[16:17] op_sel:[1,0]
